# sample-row routine: all split-K slab loads in flight at once
# baseline (speedup 1.0000x reference)
.Lsn_poll:
	global_load_dword v202, v1, s[12:13] sc1
	s_waitcnt vmcnt(0)
	v_readfirstlane_b32 s15, v202
	s_cmp_ge_u32 s15, s7
	s_cbranch_scc1 .Lsn_ready
	s_sleep 1
	s_add_i32 s14, s14, 1
	s_cmp_lt_u32 s14, 0x10000
	s_cbranch_scc1 .Lsn_poll
.Lsn_ready:
	v_mbcnt_lo_u32_b32 v200, -1, 0
	v_mbcnt_hi_u32_b32 v200, -1, v200
	v_lshlrev_b32_e32 v201, 3, v200
	v_lshlrev_b32_e32 v200, 4, v200
	s_load_dwordx2 s[16:17], s[54:55], 0xd8
	s_add_i32 s18, s3, 0x4000
	s_lshl_b32 s19, s18, 12
	s_waitcnt lgkmcnt(0)
	s_add_u32 s16, s16, s19
	s_addc_u32 s17, s17, 0
	global_load_dwordx4 v[6:9], v200, s[16:17] offset:0
	global_load_dwordx4 v[10:13], v200, s[16:17] offset:1024
	global_load_dwordx4 v[14:17], v200, s[16:17] offset:2048
	global_load_dwordx4 v[18:21], v200, s[16:17] offset:3072
	s_lshl_b32 s19, s3, 12
	s_add_u32 s20, s8, s19
	s_addc_u32 s21, s9, 0
	s_add_u32 s20, s20, 0x15e00000
	s_addc_u32 s21, s21, 0
	s_add_u32 s22, s20, 0x0
	s_addc_u32 s23, s21, 0
	global_load_dwordx4 v[22:25], v200, s[22:23] offset:0 sc1
	global_load_dwordx4 v[26:29], v200, s[22:23] offset:1024 sc1
	global_load_dwordx4 v[30:33], v200, s[22:23] offset:2048 sc1
	global_load_dwordx4 v[34:37], v200, s[22:23] offset:3072 sc1
	s_add_u32 s22, s20, 0x400000
	s_addc_u32 s23, s21, 0
	global_load_dwordx4 v[38:41], v200, s[22:23] offset:0 sc1
	global_load_dwordx4 v[42:45], v200, s[22:23] offset:1024 sc1
	global_load_dwordx4 v[46:49], v200, s[22:23] offset:2048 sc1
	global_load_dwordx4 v[50:53], v200, s[22:23] offset:3072 sc1
	s_add_u32 s22, s20, 0x800000
	s_addc_u32 s23, s21, 0
	global_load_dwordx4 v[54:57], v200, s[22:23] offset:0 sc1
	global_load_dwordx4 v[58:61], v200, s[22:23] offset:1024 sc1
	global_load_dwordx4 v[62:65], v200, s[22:23] offset:2048 sc1
	global_load_dwordx4 v[66:69], v200, s[22:23] offset:3072 sc1
	s_add_u32 s22, s20, 0xc00000
	s_addc_u32 s23, s21, 0
	global_load_dwordx4 v[70:73], v200, s[22:23] offset:0 sc1
	global_load_dwordx4 v[74:77], v200, s[22:23] offset:1024 sc1
	global_load_dwordx4 v[78:81], v200, s[22:23] offset:2048 sc1
	global_load_dwordx4 v[82:85], v200, s[22:23] offset:3072 sc1
	s_add_u32 s22, s20, 0x1000000
	s_addc_u32 s23, s21, 0
	global_load_dwordx4 v[86:89], v200, s[22:23] offset:0 sc1
	global_load_dwordx4 v[90:93], v200, s[22:23] offset:1024 sc1
	global_load_dwordx4 v[94:97], v200, s[22:23] offset:2048 sc1
	global_load_dwordx4 v[98:101], v200, s[22:23] offset:3072 sc1
	s_add_u32 s22, s20, 0x1400000
	s_addc_u32 s23, s21, 0
	global_load_dwordx4 v[102:105], v200, s[22:23] offset:0 sc1
	global_load_dwordx4 v[106:109], v200, s[22:23] offset:1024 sc1
	global_load_dwordx4 v[110:113], v200, s[22:23] offset:2048 sc1
	global_load_dwordx4 v[114:117], v200, s[22:23] offset:3072 sc1
	s_add_u32 s22, s20, 0x1800000
	s_addc_u32 s23, s21, 0
	global_load_dwordx4 v[118:121], v200, s[22:23] offset:0 sc1
	global_load_dwordx4 v[122:125], v200, s[22:23] offset:1024 sc1
	global_load_dwordx4 v[126:129], v200, s[22:23] offset:2048 sc1
	global_load_dwordx4 v[130:133], v200, s[22:23] offset:3072 sc1
	s_add_u32 s22, s20, 0x1c00000
	s_addc_u32 s23, s21, 0
	global_load_dwordx4 v[134:137], v200, s[22:23] offset:0 sc1
	global_load_dwordx4 v[138:141], v200, s[22:23] offset:1024 sc1
	global_load_dwordx4 v[142:145], v200, s[22:23] offset:2048 sc1
	global_load_dwordx4 v[146:149], v200, s[22:23] offset:3072 sc1
	s_cmp_lg_u32 s7, 44
	s_cbranch_scc1 .Lsn_l8
	s_add_u32 s22, s20, 0x2000000
	s_addc_u32 s23, s21, 0
	global_load_dwordx4 v[150:153], v200, s[22:23] offset:0 sc1
	global_load_dwordx4 v[154:157], v200, s[22:23] offset:1024 sc1
	global_load_dwordx4 v[158:161], v200, s[22:23] offset:2048 sc1
	global_load_dwordx4 v[162:165], v200, s[22:23] offset:3072 sc1
	s_add_u32 s22, s20, 0x2400000
	s_addc_u32 s23, s21, 0
	global_load_dwordx4 v[166:169], v200, s[22:23] offset:0 sc1
	global_load_dwordx4 v[170:173], v200, s[22:23] offset:1024 sc1
	global_load_dwordx4 v[174:177], v200, s[22:23] offset:2048 sc1
	global_load_dwordx4 v[178:181], v200, s[22:23] offset:3072 sc1
	s_add_u32 s22, s20, 0x2800000
	s_addc_u32 s23, s21, 0
	global_load_dwordx4 v[182:185], v200, s[22:23] offset:0 sc1
	global_load_dwordx4 v[186:189], v200, s[22:23] offset:1024 sc1
	global_load_dwordx4 v[190:193], v200, s[22:23] offset:2048 sc1
	global_load_dwordx4 v[194:197], v200, s[22:23] offset:3072 sc1
.Lsn_l8:
	s_waitcnt vmcnt(0)
	v_pk_add_f32 v[6:7], v[6:7], v[22:23]
	v_pk_add_f32 v[8:9], v[8:9], v[24:25]
	v_pk_add_f32 v[10:11], v[10:11], v[26:27]
	v_pk_add_f32 v[12:13], v[12:13], v[28:29]
	v_pk_add_f32 v[14:15], v[14:15], v[30:31]
	v_pk_add_f32 v[16:17], v[16:17], v[32:33]
	v_pk_add_f32 v[18:19], v[18:19], v[34:35]
	v_pk_add_f32 v[20:21], v[20:21], v[36:37]
	v_pk_add_f32 v[6:7], v[6:7], v[38:39]
	v_pk_add_f32 v[8:9], v[8:9], v[40:41]
	v_pk_add_f32 v[10:11], v[10:11], v[42:43]
	v_pk_add_f32 v[12:13], v[12:13], v[44:45]
	v_pk_add_f32 v[14:15], v[14:15], v[46:47]
	v_pk_add_f32 v[16:17], v[16:17], v[48:49]
	v_pk_add_f32 v[18:19], v[18:19], v[50:51]
	v_pk_add_f32 v[20:21], v[20:21], v[52:53]
	v_pk_add_f32 v[6:7], v[6:7], v[54:55]
	v_pk_add_f32 v[8:9], v[8:9], v[56:57]
	v_pk_add_f32 v[10:11], v[10:11], v[58:59]
	v_pk_add_f32 v[12:13], v[12:13], v[60:61]
	v_pk_add_f32 v[14:15], v[14:15], v[62:63]
	v_pk_add_f32 v[16:17], v[16:17], v[64:65]
	v_pk_add_f32 v[18:19], v[18:19], v[66:67]
	v_pk_add_f32 v[20:21], v[20:21], v[68:69]
	v_pk_add_f32 v[6:7], v[6:7], v[70:71]
	v_pk_add_f32 v[8:9], v[8:9], v[72:73]
	v_pk_add_f32 v[10:11], v[10:11], v[74:75]
	v_pk_add_f32 v[12:13], v[12:13], v[76:77]
	v_pk_add_f32 v[14:15], v[14:15], v[78:79]
	v_pk_add_f32 v[16:17], v[16:17], v[80:81]
	v_pk_add_f32 v[18:19], v[18:19], v[82:83]
	v_pk_add_f32 v[20:21], v[20:21], v[84:85]
	v_pk_add_f32 v[6:7], v[6:7], v[86:87]
	v_pk_add_f32 v[8:9], v[8:9], v[88:89]
	v_pk_add_f32 v[10:11], v[10:11], v[90:91]
	v_pk_add_f32 v[12:13], v[12:13], v[92:93]
	v_pk_add_f32 v[14:15], v[14:15], v[94:95]
	v_pk_add_f32 v[16:17], v[16:17], v[96:97]
	v_pk_add_f32 v[18:19], v[18:19], v[98:99]
	v_pk_add_f32 v[20:21], v[20:21], v[100:101]
	v_pk_add_f32 v[6:7], v[6:7], v[102:103]
	v_pk_add_f32 v[8:9], v[8:9], v[104:105]
	v_pk_add_f32 v[10:11], v[10:11], v[106:107]
	v_pk_add_f32 v[12:13], v[12:13], v[108:109]
	v_pk_add_f32 v[14:15], v[14:15], v[110:111]
	v_pk_add_f32 v[16:17], v[16:17], v[112:113]
	v_pk_add_f32 v[18:19], v[18:19], v[114:115]
	v_pk_add_f32 v[20:21], v[20:21], v[116:117]
	v_pk_add_f32 v[6:7], v[6:7], v[118:119]
	v_pk_add_f32 v[8:9], v[8:9], v[120:121]
	v_pk_add_f32 v[10:11], v[10:11], v[122:123]
	v_pk_add_f32 v[12:13], v[12:13], v[124:125]
	v_pk_add_f32 v[14:15], v[14:15], v[126:127]
	v_pk_add_f32 v[16:17], v[16:17], v[128:129]
	v_pk_add_f32 v[18:19], v[18:19], v[130:131]
	v_pk_add_f32 v[20:21], v[20:21], v[132:133]
	v_pk_add_f32 v[6:7], v[6:7], v[134:135]
	v_pk_add_f32 v[8:9], v[8:9], v[136:137]
	v_pk_add_f32 v[10:11], v[10:11], v[138:139]
	v_pk_add_f32 v[12:13], v[12:13], v[140:141]
	v_pk_add_f32 v[14:15], v[14:15], v[142:143]
	v_pk_add_f32 v[16:17], v[16:17], v[144:145]
	v_pk_add_f32 v[18:19], v[18:19], v[146:147]
	v_pk_add_f32 v[20:21], v[20:21], v[148:149]
	s_cmp_lg_u32 s7, 44
	s_cbranch_scc1 .Lsn_sum
	v_pk_add_f32 v[6:7], v[6:7], v[150:151]
	v_pk_add_f32 v[8:9], v[8:9], v[152:153]
	v_pk_add_f32 v[10:11], v[10:11], v[154:155]
	v_pk_add_f32 v[12:13], v[12:13], v[156:157]
	v_pk_add_f32 v[14:15], v[14:15], v[158:159]
	v_pk_add_f32 v[16:17], v[16:17], v[160:161]
	v_pk_add_f32 v[18:19], v[18:19], v[162:163]
	v_pk_add_f32 v[20:21], v[20:21], v[164:165]
	v_pk_add_f32 v[6:7], v[6:7], v[166:167]
	v_pk_add_f32 v[8:9], v[8:9], v[168:169]
	v_pk_add_f32 v[10:11], v[10:11], v[170:171]
	v_pk_add_f32 v[12:13], v[12:13], v[172:173]
	v_pk_add_f32 v[14:15], v[14:15], v[174:175]
	v_pk_add_f32 v[16:17], v[16:17], v[176:177]
	v_pk_add_f32 v[18:19], v[18:19], v[178:179]
	v_pk_add_f32 v[20:21], v[20:21], v[180:181]
	v_pk_add_f32 v[6:7], v[6:7], v[182:183]
	v_pk_add_f32 v[8:9], v[8:9], v[184:185]
	v_pk_add_f32 v[10:11], v[10:11], v[186:187]
	v_pk_add_f32 v[12:13], v[12:13], v[188:189]
	v_pk_add_f32 v[14:15], v[14:15], v[190:191]
	v_pk_add_f32 v[16:17], v[16:17], v[192:193]
	v_pk_add_f32 v[18:19], v[18:19], v[194:195]
	v_pk_add_f32 v[20:21], v[20:21], v[196:197]

.Lsn_p_done:
	s_load_dwordx2 s[28:29], s[54:55], s26
	s_lshl_b32 s24, s24, 12
	s_waitcnt lgkmcnt(0)
	s_add_u32 s28, s28, s24
	s_addc_u32 s29, s29, 0
	global_load_dwordx4 v[22:25], v200, s[28:29] offset:0
	global_load_dwordx4 v[26:29], v200, s[28:29] offset:1024
	global_load_dwordx4 v[30:33], v200, s[28:29] offset:2048
	global_load_dwordx4 v[34:37], v200, s[28:29] offset:3072
	v_mov_b32_e32 v38, 0
	v_mov_b32_e32 v54, 0
	v_mov_b32_e32 v39, 0
	v_mov_b32_e32 v55, 0
	v_mov_b32_e32 v40, 0
	v_mov_b32_e32 v56, 0
	v_mov_b32_e32 v41, 0
	v_mov_b32_e32 v57, 0
	v_mov_b32_e32 v42, 0
	v_mov_b32_e32 v58, 0
	v_mov_b32_e32 v43, 0
	v_mov_b32_e32 v59, 0
	v_mov_b32_e32 v44, 0
	v_mov_b32_e32 v60, 0
	v_mov_b32_e32 v45, 0
	v_mov_b32_e32 v61, 0
	v_mov_b32_e32 v46, 0
	v_mov_b32_e32 v62, 0
	v_mov_b32_e32 v47, 0
	v_mov_b32_e32 v63, 0
	v_mov_b32_e32 v48, 0
	v_mov_b32_e32 v64, 0
	v_mov_b32_e32 v49, 0
	v_mov_b32_e32 v65, 0
	v_mov_b32_e32 v50, 0
	v_mov_b32_e32 v66, 0
	v_mov_b32_e32 v51, 0
	v_mov_b32_e32 v67, 0
	v_mov_b32_e32 v52, 0
	v_mov_b32_e32 v68, 0
	v_mov_b32_e32 v53, 0
	v_mov_b32_e32 v69, 0
	s_cmp_eq_u32 s5, 7
	s_cbranch_scc1 .Lsn_nomod
	v_readlane_b32 s28, v253, 34
	v_readlane_b32 s29, v253, 35
	s_lshr_b32 s30, s3, 3
	s_add_i32 s30, s30, 2
	s_mul_i32 s30, s30, 0x18000
	s_add_i32 s30, s30, s27
	s_add_u32 s28, s28, s30
	s_addc_u32 s29, s29, 0
	global_load_dwordx4 v[38:41], v200, s[28:29] offset:0
	global_load_dwordx4 v[42:45], v200, s[28:29] offset:1024
	global_load_dwordx4 v[46:49], v200, s[28:29] offset:2048
	global_load_dwordx4 v[50:53], v200, s[28:29] offset:3072
	s_add_u32 s28, s28, 0x1000
	s_addc_u32 s29, s29, 0
	global_load_dwordx4 v[54:57], v200, s[28:29] offset:0
	global_load_dwordx4 v[58:61], v200, s[28:29] offset:1024
	global_load_dwordx4 v[62:65], v200, s[28:29] offset:2048
	global_load_dwordx4 v[66:69], v200, s[28:29] offset:3072
.Lsn_nomod:
	v_pk_mul_f32 v[202:203], v[6:7], v[6:7]
	v_pk_fma_f32 v[202:203], v[8:9], v[8:9], v[202:203]
	v_pk_fma_f32 v[202:203], v[10:11], v[10:11], v[202:203]
	v_pk_fma_f32 v[202:203], v[12:13], v[12:13], v[202:203]
	v_pk_fma_f32 v[202:203], v[14:15], v[14:15], v[202:203]
	v_pk_fma_f32 v[202:203], v[16:17], v[16:17], v[202:203]
	v_pk_fma_f32 v[202:203], v[18:19], v[18:19], v[202:203]
	v_pk_fma_f32 v[202:203], v[20:21], v[20:21], v[202:203]
	v_add_f32_e32 v202, v202, v203
	s_nop 1
	v_add_f32_dpp v202, v202, v202 quad_perm:[1,0,3,2] row_mask:0xf bank_mask:0xf
	s_nop 1
	v_add_f32_dpp v202, v202, v202 quad_perm:[2,3,0,1] row_mask:0xf bank_mask:0xf
	s_nop 1
	v_add_f32_dpp v202, v202, v202 row_half_mirror row_mask:0xf bank_mask:0xf
	s_nop 1
	v_add_f32_dpp v202, v202, v202 row_mirror row_mask:0xf bank_mask:0xf
	s_nop 1
	v_add_f32_dpp v202, v202, v202 row_bcast:15 row_mask:0xa bank_mask:0xf
	s_nop 1
	v_add_f32_dpp v202, v202, v202 row_bcast:31 row_mask:0xc bank_mask:0xf
	s_nop 1
	v_readlane_b32 s30, v202, 63
	s_nop 1
	v_mov_b32_e32 v204, s30
	v_fmamk_f32 v204, v204, 0x3a800000, v232
	v_rsq_f32_e32 v204, v204
	s_nop 0
	v_mov_b32_e32 v205, v204
	s_waitcnt vmcnt(0)
	s_lshl_b32 s19, s18, 11
	s_add_u32 s30, s8, s19
	s_addc_u32 s31, s9, 0
	s_add_u32 s30, s30, 0x7400000
	s_addc_u32 s31, s31, 0
	s_cmp_eq_u32 s5, 7
	s_cbranch_scc1 .Lsn_final_out
	global_store_dwordx4 v200, v[6:9], s[16:17] offset:0
	global_store_dwordx4 v200, v[10:13], s[16:17] offset:1024
	global_store_dwordx4 v200, v[14:17], s[16:17] offset:2048
	global_store_dwordx4 v200, v[18:21], s[16:17] offset:3072
	v_pk_add_f32 v[54:55], v[54:55], 1.0 op_sel_hi:[1,0]
	v_pk_mul_f32 v[22:23], v[22:23], v[54:55]
	v_pk_mul_f32 v[206:207], v[6:7], v[204:205]
	v_pk_fma_f32 v[206:207], v[206:207], v[22:23], v[38:39]
	v_pk_add_f32 v[56:57], v[56:57], 1.0 op_sel_hi:[1,0]
	v_pk_mul_f32 v[24:25], v[24:25], v[56:57]
	v_pk_mul_f32 v[208:209], v[8:9], v[204:205]
	v_pk_fma_f32 v[208:209], v[208:209], v[24:25], v[40:41]
	v_cvt_pk_bf16_f32 v210, v206, v207
	v_cvt_pk_bf16_f32 v211, v208, v209
	global_store_dwordx2 v201, v[210:211], s[30:31] offset:0
	v_pk_add_f32 v[58:59], v[58:59], 1.0 op_sel_hi:[1,0]
	v_pk_mul_f32 v[26:27], v[26:27], v[58:59]
	v_pk_mul_f32 v[206:207], v[10:11], v[204:205]
	v_pk_fma_f32 v[206:207], v[206:207], v[26:27], v[42:43]
	v_pk_add_f32 v[60:61], v[60:61], 1.0 op_sel_hi:[1,0]
	v_pk_mul_f32 v[28:29], v[28:29], v[60:61]
	v_pk_mul_f32 v[208:209], v[12:13], v[204:205]
	v_pk_fma_f32 v[208:209], v[208:209], v[28:29], v[44:45]
	v_cvt_pk_bf16_f32 v212, v206, v207
	v_cvt_pk_bf16_f32 v213, v208, v209
	global_store_dwordx2 v201, v[212:213], s[30:31] offset:512
	v_pk_add_f32 v[62:63], v[62:63], 1.0 op_sel_hi:[1,0]
	v_pk_mul_f32 v[30:31], v[30:31], v[62:63]
	v_pk_mul_f32 v[206:207], v[14:15], v[204:205]
	v_pk_fma_f32 v[206:207], v[206:207], v[30:31], v[46:47]
	v_pk_add_f32 v[64:65], v[64:65], 1.0 op_sel_hi:[1,0]
	v_pk_mul_f32 v[32:33], v[32:33], v[64:65]
	v_pk_mul_f32 v[208:209], v[16:17], v[204:205]
	v_pk_fma_f32 v[208:209], v[208:209], v[32:33], v[48:49]
	v_cvt_pk_bf16_f32 v214, v206, v207
	v_cvt_pk_bf16_f32 v215, v208, v209
	global_store_dwordx2 v201, v[214:215], s[30:31] offset:1024
	v_pk_add_f32 v[66:67], v[66:67], 1.0 op_sel_hi:[1,0]
	v_pk_mul_f32 v[34:35], v[34:35], v[66:67]
	v_pk_mul_f32 v[206:207], v[18:19], v[204:205]
	v_pk_fma_f32 v[206:207], v[206:207], v[34:35], v[50:51]
	v_pk_add_f32 v[68:69], v[68:69], 1.0 op_sel_hi:[1,0]
	v_pk_mul_f32 v[36:37], v[36:37], v[68:69]
	v_pk_mul_f32 v[208:209], v[20:21], v[204:205]
	v_pk_fma_f32 v[208:209], v[208:209], v[36:37], v[52:53]
	v_cvt_pk_bf16_f32 v216, v206, v207
	v_cvt_pk_bf16_f32 v217, v208, v209
	global_store_dwordx2 v201, v[216:217], s[30:31] offset:1536
	s_branch .Lsn_done
.Lsn_final_out:
	v_pk_mul_f32 v[6:7], v[6:7], v[204:205]
	v_pk_mul_f32 v[6:7], v[6:7], v[22:23]
	v_pk_mul_f32 v[8:9], v[8:9], v[204:205]
	v_pk_mul_f32 v[8:9], v[8:9], v[24:25]
	global_store_dwordx4 v200, v[6:9], s[16:17] offset:0
	v_pk_mul_f32 v[10:11], v[10:11], v[204:205]
	v_pk_mul_f32 v[10:11], v[10:11], v[26:27]
	v_pk_mul_f32 v[12:13], v[12:13], v[204:205]
	v_pk_mul_f32 v[12:13], v[12:13], v[28:29]
	global_store_dwordx4 v200, v[10:13], s[16:17] offset:1024
	v_pk_mul_f32 v[14:15], v[14:15], v[204:205]
	v_pk_mul_f32 v[14:15], v[14:15], v[30:31]
	v_pk_mul_f32 v[16:17], v[16:17], v[204:205]
	v_pk_mul_f32 v[16:17], v[16:17], v[32:33]
	global_store_dwordx4 v200, v[14:17], s[16:17] offset:2048
	v_pk_mul_f32 v[18:19], v[18:19], v[204:205]
	v_pk_mul_f32 v[18:19], v[18:19], v[34:35]
	v_pk_mul_f32 v[20:21], v[20:21], v[204:205]
	v_pk_mul_f32 v[20:21], v[20:21], v[36:37]
	global_store_dwordx4 v200, v[18:21], s[16:17] offset:3072
